# static priority 3 (was 1) for waves 4-7 inside the K-loops
# speedup vs baseline: 1.0035x; 1.0035x over previous
.LBB0_130:
	s_ashr_i32 s13, s12, 31
	v_cmp_lt_i64_e32 vcc, s[14:15], v[140:141]
	s_lshl_b64 s[14:15], s[12:13], 19
	s_add_u32 s14, s39, s14
	s_addc_u32 s15, s40, s15
	s_and_b64 s[16:17], vcc, exec
	s_cselect_b32 s13, s15, s21
	s_cselect_b32 s53, s14, s20
	s_ashr_i32 s11, s10, 31
	s_lshl_b64 s[16:17], s[10:11], 19
	s_add_u32 s16, s33, s16
	s_addc_u32 s17, s34, s17
	s_and_b64 s[28:29], vcc, exec
	s_cselect_b32 s11, s17, s27
	s_cselect_b32 s54, s16, s26
	s_add_u32 s20, s20, 0x40080
	s_addc_u32 s21, s21, 0
	s_add_u32 s55, s26, 0x100
	s_addc_u32 s56, s27, 0
	s_mov_b32 s57, -2
	s_setprio 0
	s_cmpk_lt_u32 s37, 0x100
	s_cbranch_scc1 .Lg131_noy
	s_setprio 3
	s_barrier

.LBB0_247:
	s_add_u32 s57, s26, 0x100
	s_addc_u32 s58, s27, 0
	s_mov_b32 s59, -2
	s_waitcnt lgkmcnt(0)
	s_setprio 0
	s_cmpk_lt_u32 s35, 0x100
	s_cbranch_scc1 .Lg248_noy
	s_setprio 3
	s_barrier

.LBB0_358:
	s_ashr_i32 s21, s20, 31
	v_cmp_lt_i64_e32 vcc, s[30:31], v[162:163]
	s_lshl_b64 s[30:31], s[20:21], 19
	s_add_u32 s30, s47, s30
	s_addc_u32 s31, s48, s31
	s_and_b64 s[34:35], vcc, exec
	s_cselect_b32 s21, s31, s9
	s_cselect_b32 s71, s30, s8
	s_ashr_i32 s19, s18, 31
	s_lshl_b64 s[34:35], s[18:19], 19
	s_add_u32 s34, s49, s34
	s_addc_u32 s35, s50, s35
	s_and_b64 s[40:41], vcc, exec
	s_cselect_b32 s19, s35, s39
	s_cselect_b32 s72, s34, s38
	s_add_u32 s8, s8, 0x40080
	s_addc_u32 s9, s9, 0
	s_add_u32 s73, s38, 0x100
	s_addc_u32 s74, s39, 0
	s_mov_b32 s75, -2
	s_setprio 0
	s_cmpk_lt_u32 s45, 0x100
	s_cbranch_scc1 .Lg359_noy
	s_setprio 3
	s_barrier

.LBB0_785:
	s_ashr_i32 s19, s18, 31
	v_cmp_lt_i64_e32 vcc, s[20:21], v[140:141]
	s_lshl_b64 s[20:21], s[18:19], 19
	s_add_u32 s20, s38, s20
	s_addc_u32 s21, s39, s21
	s_and_b64 s[26:27], vcc, exec
	s_cselect_b32 s19, s21, s29
	s_cselect_b32 s57, s20, s28
	s_ashr_i32 s17, s16, 31
	s_lshl_b64 s[26:27], s[16:17], 19
	s_add_u32 s26, s40, s26
	s_addc_u32 s27, s41, s27
	s_and_b64 s[34:35], vcc, exec
	s_cselect_b32 s17, s27, s31
	s_cselect_b32 s58, s26, s30
	s_add_u32 s28, s28, 0x40080
	s_addc_u32 s29, s29, 0
	s_add_u32 s59, s30, 0x100
	s_addc_u32 s60, s31, 0
	s_mov_b32 s61, -2
	s_waitcnt lgkmcnt(0)
	s_setprio 0
	s_cmpk_lt_u32 s37, 0x100
	s_cbranch_scc1 .Lg786_noy
	s_setprio 3
	s_barrier

.LBB0_892:
	s_ashr_i32 s13, s12, 31
	v_cmp_lt_i64_e32 vcc, s[14:15], v[140:141]
	s_lshl_b64 s[14:15], s[12:13], 19
	s_add_u32 s14, s37, s14
	s_addc_u32 s15, s38, s15
	s_and_b64 s[16:17], vcc, exec
	s_cselect_b32 s13, s15, s21
	s_cselect_b32 s53, s14, s20
	s_ashr_i32 s11, s10, 31
	s_lshl_b64 s[16:17], s[10:11], 19
	s_add_u32 s16, s39, s16
	s_addc_u32 s17, s40, s17
	s_and_b64 s[28:29], vcc, exec
	s_cselect_b32 s11, s17, s27
	s_cselect_b32 s54, s16, s26
	s_add_u32 s20, s20, 0x40080
	s_addc_u32 s21, s21, 0
	s_add_u32 s55, s26, 0x100
	s_addc_u32 s56, s27, 0
	s_mov_b32 s57, -2
	s_setprio 0
	s_cmpk_lt_u32 s30, 0x100
	s_cbranch_scc1 .Lg893_noy
	s_setprio 3
	s_barrier

.LBB0_972:
	s_add_u32 s54, s22, 0x100
	s_addc_u32 s55, s23, 0
	s_mov_b32 s56, -2
	s_setprio 0
	s_cmpk_lt_u32 s30, 0x100
	s_cbranch_scc1 .Lg973_noy
	s_setprio 3
	s_barrier
